# attention: K and V in blocked layouts written by phase 2 (1 KiB contiguous per fragment load, 16-byte V loads with parity-dependent tile pairing)
# baseline (speedup 1.0000x reference)
.LBB0_186:
	s_or_b64 exec, exec, s[50:51]
	s_waitcnt vmcnt(36)
	v_lshlrev_b32_e32 v64, 16, v129
	v_and_b32_e32 v65, 0xffff0000, v129
	s_waitcnt vmcnt(35)
	v_lshlrev_b32_e32 v66, 16, v128
	v_and_b32_e32 v67, 0xffff0000, v128
	v_pk_mul_f32 v[60:61], v[64:65], v[64:65]
	v_pk_mul_f32 v[62:63], v[66:67], v[66:67]
	v_mov_b32_e32 v69, v60
	v_mov_b32_e32 v68, v62
	v_mov_b32_e32 v60, v63
	v_pk_add_f32 v[60:61], v[68:69], v[60:61]
	v_add_u32_e32 v1, s18, v1
	v_lshl_add_u64 v[50:51], v[50:51], 0, s[20:21]
	v_mov_b32_dpp v63, v61 quad_perm:[1,0,3,2] row_mask:0xf bank_mask:0xf bound_ctrl:1
	v_mov_b32_dpp v62, v60 quad_perm:[1,0,3,2] row_mask:0xf bank_mask:0xf bound_ctrl:1
	v_pk_add_f32 v[60:61], v[60:61], v[62:63]
	v_lshl_add_u64 v[56:57], v[56:57], 0, s[26:27]
	v_lshl_add_u64 v[58:59], v[58:59], 0, s[28:29]
	v_mov_b32_dpp v63, v61 quad_perm:[2,3,0,1] row_mask:0xf bank_mask:0xf bound_ctrl:1
	v_mov_b32_dpp v62, v60 quad_perm:[2,3,0,1] row_mask:0xf bank_mask:0xf bound_ctrl:1
	v_pk_add_f32 v[60:61], v[60:61], v[62:63]
	s_nop 1
	v_mov_b32_dpp v63, v61 row_half_mirror row_mask:0xf bank_mask:0xf bound_ctrl:1
	v_mov_b32_dpp v62, v60 row_half_mirror row_mask:0xf bank_mask:0xf bound_ctrl:1
	v_pk_add_f32 v[60:61], v[60:61], v[62:63]
	s_nop 1
	v_mov_b32_dpp v63, v61 row_mirror row_mask:0xf bank_mask:0xf bound_ctrl:1
	v_mov_b32_dpp v62, v60 row_mirror row_mask:0xf bank_mask:0xf bound_ctrl:1
	v_pk_add_f32 v[60:61], v[60:61], v[62:63]
	ds_bpermute_b32 v63, v120, v61
	ds_bpermute_b32 v62, v120, v60
	s_waitcnt lgkmcnt(0)
	v_pk_add_f32 v[60:61], v[60:61], v[62:63]
	v_mov_b64_e32 v[62:63], s[46:47]
	v_pk_fma_f32 v[68:69], v[60:61], s[42:43], v[62:63] op_sel_hi:[1,0,0]
	s_nop 0
	v_mul_f32_e32 v60, 0x4b800000, v69
	v_cmp_gt_f32_e32 vcc, s72, v69
	s_nop 1
	v_cndmask_b32_e32 v60, v69, v60, vcc
	v_rsq_f32_e32 v69, v60
	v_lshl_add_u64 v[60:61], v[52:53], 0, v[2:3]
	v_lshl_add_u64 v[52:53], v[52:53], 0, s[22:23]
	v_mul_f32_e32 v70, 0x45800000, v69
	v_cndmask_b32_e32 v70, v69, v70, vcc
	v_pk_mul_f32 v[64:65], v[70:71], v[64:65] op_sel_hi:[0,1]
	v_pk_mul_f32 v[64:65], v[48:49], v[64:65]
	v_cmp_gt_f32_e32 vcc, s72, v68
	v_cvt_pk_bf16_f32 v76, v64, v65
	v_mul_f32_e32 v64, 0x4b800000, v68
	v_cndmask_b32_e32 v64, v68, v64, vcc
	v_rsq_f32_e32 v77, v64
	s_waitcnt vmcnt(34)
	v_lshlrev_b32_e32 v64, 16, v127
	v_and_b32_e32 v65, 0xffff0000, v127
	s_waitcnt vmcnt(33)
	v_lshlrev_b32_e32 v70, 16, v126
	v_and_b32_e32 v71, 0xffff0000, v126
	v_pk_mul_f32 v[68:69], v[64:65], v[64:65]
	v_pk_mul_f32 v[72:73], v[70:71], v[70:71]
	v_mov_b32_e32 v75, v68
	v_mov_b32_e32 v74, v72
	v_mov_b32_e32 v68, v73
	v_pk_add_f32 v[68:69], v[74:75], v[68:69]
	v_mul_f32_e32 v74, 0x45800000, v77
	v_cndmask_b32_e32 v74, v77, v74, vcc
	v_mov_b32_dpp v73, v69 quad_perm:[1,0,3,2] row_mask:0xf bank_mask:0xf bound_ctrl:1
	v_mov_b32_dpp v72, v68 quad_perm:[1,0,3,2] row_mask:0xf bank_mask:0xf bound_ctrl:1
	v_pk_add_f32 v[68:69], v[68:69], v[72:73]
	v_pk_mul_f32 v[66:67], v[74:75], v[66:67] op_sel_hi:[0,1]
	v_pk_mul_f32 v[66:67], v[48:49], v[66:67]
	v_mov_b32_dpp v73, v69 quad_perm:[2,3,0,1] row_mask:0xf bank_mask:0xf bound_ctrl:1
	v_mov_b32_dpp v72, v68 quad_perm:[2,3,0,1] row_mask:0xf bank_mask:0xf bound_ctrl:1
	v_pk_add_f32 v[68:69], v[68:69], v[72:73]
	v_cvt_pk_bf16_f32 v66, v66, v67
	global_store_dword v[60:61], v66, off offset:-768
	v_mov_b32_dpp v73, v69 row_half_mirror row_mask:0xf bank_mask:0xf bound_ctrl:1
	v_mov_b32_dpp v72, v68 row_half_mirror row_mask:0xf bank_mask:0xf bound_ctrl:1
	v_pk_add_f32 v[68:69], v[68:69], v[72:73]
	global_store_dword v[60:61], v76, off offset:-1024
	s_nop 0
	v_mov_b32_dpp v73, v69 row_mirror row_mask:0xf bank_mask:0xf bound_ctrl:1
	v_mov_b32_dpp v72, v68 row_mirror row_mask:0xf bank_mask:0xf bound_ctrl:1
	v_pk_add_f32 v[68:69], v[68:69], v[72:73]
	ds_bpermute_b32 v73, v120, v69
	ds_bpermute_b32 v72, v120, v68
	s_waitcnt lgkmcnt(0)
	v_pk_add_f32 v[68:69], v[68:69], v[72:73]
	s_nop 0
	v_pk_fma_f32 v[68:69], v[68:69], s[42:43], v[62:63] op_sel_hi:[1,0,0]
	s_nop 0
	v_mul_f32_e32 v72, 0x4b800000, v69
	v_cmp_gt_f32_e32 vcc, s72, v69
	s_nop 1
	v_cndmask_b32_e32 v69, v69, v72, vcc
	v_rsq_f32_e32 v69, v69
	s_nop 0
	v_mul_f32_e32 v66, 0x45800000, v69
	v_cndmask_b32_e32 v66, v69, v66, vcc
	v_pk_mul_f32 v[64:65], v[66:67], v[64:65] op_sel_hi:[0,1]
	v_pk_mul_f32 v[64:65], v[48:49], v[64:65]
	v_cmp_gt_f32_e32 vcc, s72, v68
	v_cvt_pk_bf16_f32 v76, v64, v65
	v_mul_f32_e32 v64, 0x4b800000, v68
	v_cndmask_b32_e32 v64, v68, v64, vcc
	v_rsq_f32_e32 v77, v64
	s_waitcnt vmcnt(34)
	v_lshlrev_b32_e32 v64, 16, v125
	v_and_b32_e32 v65, 0xffff0000, v125
	s_waitcnt vmcnt(33)
	v_lshlrev_b32_e32 v68, 16, v124
	v_and_b32_e32 v69, 0xffff0000, v124
	v_pk_mul_f32 v[66:67], v[64:65], v[64:65]
	v_pk_mul_f32 v[72:73], v[68:69], v[68:69]
	v_mov_b32_e32 v75, v66
	v_mov_b32_e32 v74, v72
	v_mov_b32_e32 v66, v73
	v_pk_add_f32 v[66:67], v[74:75], v[66:67]
	v_mul_f32_e32 v74, 0x45800000, v77
	v_cndmask_b32_e32 v74, v77, v74, vcc
	v_mov_b32_dpp v73, v67 quad_perm:[1,0,3,2] row_mask:0xf bank_mask:0xf bound_ctrl:1
	v_mov_b32_dpp v72, v66 quad_perm:[1,0,3,2] row_mask:0xf bank_mask:0xf bound_ctrl:1
	v_pk_add_f32 v[66:67], v[66:67], v[72:73]
	v_pk_mul_f32 v[70:71], v[74:75], v[70:71] op_sel_hi:[0,1]
	v_pk_mul_f32 v[70:71], v[48:49], v[70:71]
	v_mov_b32_dpp v73, v67 quad_perm:[2,3,0,1] row_mask:0xf bank_mask:0xf bound_ctrl:1
	v_mov_b32_dpp v72, v66 quad_perm:[2,3,0,1] row_mask:0xf bank_mask:0xf bound_ctrl:1
	v_pk_add_f32 v[66:67], v[66:67], v[72:73]
	v_cvt_pk_bf16_f32 v70, v70, v71
	global_store_dword v[60:61], v70, off offset:-256
	v_mov_b32_dpp v73, v67 row_half_mirror row_mask:0xf bank_mask:0xf bound_ctrl:1
	v_mov_b32_dpp v72, v66 row_half_mirror row_mask:0xf bank_mask:0xf bound_ctrl:1
	v_pk_add_f32 v[66:67], v[66:67], v[72:73]
	global_store_dword v[60:61], v76, off offset:-512
	s_nop 0
	v_mov_b32_dpp v73, v67 row_mirror row_mask:0xf bank_mask:0xf bound_ctrl:1
	v_mov_b32_dpp v72, v66 row_mirror row_mask:0xf bank_mask:0xf bound_ctrl:1
	v_pk_add_f32 v[66:67], v[66:67], v[72:73]
	ds_bpermute_b32 v73, v120, v67
	ds_bpermute_b32 v72, v120, v66
	s_waitcnt lgkmcnt(0)
	v_pk_add_f32 v[66:67], v[66:67], v[72:73]
	s_nop 0
	v_pk_fma_f32 v[66:67], v[66:67], s[42:43], v[62:63] op_sel_hi:[1,0,0]
	s_nop 0
	v_mul_f32_e32 v72, 0x4b800000, v67
	v_cmp_gt_f32_e32 vcc, s72, v67
	s_nop 1
	v_cndmask_b32_e32 v67, v67, v72, vcc
	v_rsq_f32_e32 v67, v67
	s_nop 0
	v_mul_f32_e32 v70, 0x45800000, v67
	v_cndmask_b32_e32 v70, v67, v70, vcc
	v_pk_mul_f32 v[64:65], v[70:71], v[64:65] op_sel_hi:[0,1]
	v_pk_mul_f32 v[64:65], v[48:49], v[64:65]
	v_cmp_gt_f32_e32 vcc, s72, v66
	v_cvt_pk_bf16_f32 v76, v64, v65
	v_mul_f32_e32 v64, 0x4b800000, v66
	v_cndmask_b32_e32 v64, v66, v64, vcc
	v_rsq_f32_e32 v77, v64
	s_waitcnt vmcnt(34)
	v_lshlrev_b32_e32 v64, 16, v119
	v_and_b32_e32 v65, 0xffff0000, v119
	s_waitcnt vmcnt(33)
	v_lshlrev_b32_e32 v70, 16, v118
	v_and_b32_e32 v71, 0xffff0000, v118
	v_pk_mul_f32 v[66:67], v[64:65], v[64:65]
	v_pk_mul_f32 v[72:73], v[70:71], v[70:71]
	v_mov_b32_e32 v75, v66
	v_mov_b32_e32 v74, v72
	v_mov_b32_e32 v66, v73
	v_pk_add_f32 v[66:67], v[74:75], v[66:67]
	v_mul_f32_e32 v74, 0x45800000, v77
	v_cndmask_b32_e32 v74, v77, v74, vcc
	v_mov_b32_dpp v73, v67 quad_perm:[1,0,3,2] row_mask:0xf bank_mask:0xf bound_ctrl:1
	v_mov_b32_dpp v72, v66 quad_perm:[1,0,3,2] row_mask:0xf bank_mask:0xf bound_ctrl:1
	v_pk_add_f32 v[66:67], v[66:67], v[72:73]
	v_pk_mul_f32 v[68:69], v[74:75], v[68:69] op_sel_hi:[0,1]
	v_pk_mul_f32 v[68:69], v[48:49], v[68:69]
	v_mov_b32_dpp v73, v67 quad_perm:[2,3,0,1] row_mask:0xf bank_mask:0xf bound_ctrl:1
	v_mov_b32_dpp v72, v66 quad_perm:[2,3,0,1] row_mask:0xf bank_mask:0xf bound_ctrl:1
	v_pk_add_f32 v[66:67], v[66:67], v[72:73]
	v_cvt_pk_bf16_f32 v68, v68, v69
	global_store_dword v[60:61], v68, off offset:256
	v_mov_b32_dpp v73, v67 row_half_mirror row_mask:0xf bank_mask:0xf bound_ctrl:1
	v_mov_b32_dpp v72, v66 row_half_mirror row_mask:0xf bank_mask:0xf bound_ctrl:1
	v_pk_add_f32 v[66:67], v[66:67], v[72:73]
	global_store_dword v[60:61], v76, off
	s_nop 0
	v_mov_b32_dpp v73, v67 row_mirror row_mask:0xf bank_mask:0xf bound_ctrl:1
	v_mov_b32_dpp v72, v66 row_mirror row_mask:0xf bank_mask:0xf bound_ctrl:1
	v_pk_add_f32 v[66:67], v[66:67], v[72:73]
	ds_bpermute_b32 v73, v120, v67
	ds_bpermute_b32 v72, v120, v66
	s_waitcnt lgkmcnt(0)
	v_pk_add_f32 v[66:67], v[66:67], v[72:73]
	s_nop 0
	v_pk_fma_f32 v[66:67], v[66:67], s[42:43], v[62:63] op_sel_hi:[1,0,0]
	s_nop 0
	v_mul_f32_e32 v72, 0x4b800000, v67
	v_cmp_gt_f32_e32 vcc, s72, v67
	s_nop 1
	v_cndmask_b32_e32 v67, v67, v72, vcc
	v_rsq_f32_e32 v67, v67
	s_nop 0
	v_mul_f32_e32 v68, 0x45800000, v67
	v_cndmask_b32_e32 v68, v67, v68, vcc
	v_pk_mul_f32 v[64:65], v[68:69], v[64:65] op_sel_hi:[0,1]
	v_pk_mul_f32 v[64:65], v[48:49], v[64:65]
	v_cmp_gt_f32_e32 vcc, s72, v66
	v_cvt_pk_bf16_f32 v64, v64, v65
	global_store_dword v[60:61], v64, off offset:512
	v_mul_f32_e32 v64, 0x4b800000, v66
	v_cndmask_b32_e32 v64, v66, v64, vcc
	v_rsq_f32_e32 v76, v64
	s_waitcnt vmcnt(35)
	v_lshlrev_b32_e32 v64, 16, v117
	v_and_b32_e32 v65, 0xffff0000, v117
	s_waitcnt vmcnt(34)
	v_lshlrev_b32_e32 v68, 16, v116
	v_and_b32_e32 v69, 0xffff0000, v116
	v_pk_mul_f32 v[66:67], v[64:65], v[64:65]
	v_pk_mul_f32 v[72:73], v[68:69], v[68:69]
	v_mov_b32_e32 v75, v66
	v_mov_b32_e32 v74, v72
	v_mov_b32_e32 v66, v73
	v_pk_add_f32 v[66:67], v[74:75], v[66:67]
	v_mul_f32_e32 v74, 0x45800000, v76
	v_cndmask_b32_e32 v74, v76, v74, vcc
	v_mov_b32_dpp v73, v67 quad_perm:[1,0,3,2] row_mask:0xf bank_mask:0xf bound_ctrl:1
	v_mov_b32_dpp v72, v66 quad_perm:[1,0,3,2] row_mask:0xf bank_mask:0xf bound_ctrl:1
	v_pk_add_f32 v[66:67], v[66:67], v[72:73]
	v_pk_mul_f32 v[70:71], v[74:75], v[70:71] op_sel_hi:[0,1]
	v_pk_mul_f32 v[70:71], v[48:49], v[70:71]
	v_mov_b32_dpp v73, v67 quad_perm:[2,3,0,1] row_mask:0xf bank_mask:0xf bound_ctrl:1
	v_mov_b32_dpp v72, v66 quad_perm:[2,3,0,1] row_mask:0xf bank_mask:0xf bound_ctrl:1
	v_pk_add_f32 v[66:67], v[66:67], v[72:73]
	s_nop 1
	v_mov_b32_dpp v73, v67 row_half_mirror row_mask:0xf bank_mask:0xf bound_ctrl:1
	v_mov_b32_dpp v72, v66 row_half_mirror row_mask:0xf bank_mask:0xf bound_ctrl:1
	v_pk_add_f32 v[66:67], v[66:67], v[72:73]
	s_nop 1
	v_mov_b32_dpp v73, v67 row_mirror row_mask:0xf bank_mask:0xf bound_ctrl:1
	v_mov_b32_dpp v72, v66 row_mirror row_mask:0xf bank_mask:0xf bound_ctrl:1
	v_pk_add_f32 v[66:67], v[66:67], v[72:73]
	ds_bpermute_b32 v73, v120, v67
	ds_bpermute_b32 v72, v120, v66
	s_waitcnt lgkmcnt(0)
	v_pk_add_f32 v[66:67], v[66:67], v[72:73]
	s_nop 0
	v_pk_fma_f32 v[62:63], v[66:67], s[42:43], v[62:63] op_sel_hi:[1,0,0]
	s_nop 0
	v_mul_f32_e32 v66, 0x4b800000, v63
	v_cmp_gt_f32_e32 vcc, s72, v63
	s_nop 1
	v_cndmask_b32_e32 v63, v63, v66, vcc
	v_rsq_f32_e32 v63, v63
	v_cvt_pk_bf16_f32 v66, v70, v71
	global_store_dword v[60:61], v66, off offset:768
	v_lshl_add_u64 v[60:61], v[54:55], 0, v[2:3]
	v_mul_f32_e32 v66, 0x45800000, v63
	v_cndmask_b32_e32 v66, v63, v66, vcc
	v_pk_mul_f32 v[64:65], v[66:67], v[64:65] op_sel_hi:[0,1]
	v_pk_mul_f32 v[64:65], v[6:7], v[64:65]
	v_cmp_gt_f32_e32 vcc, s72, v62
	v_cvt_pk_bf16_f32 v63, v64, v65
	v_mul_f32_e32 v64, 0x4b800000, v62
	v_cndmask_b32_e32 v62, v62, v64, vcc
	v_rsq_f32_e32 v62, v62
	v_add_co_u32_e64 v60, s[12:13], s73, v60
	v_lshl_add_u64 v[54:55], v[54:55], 0, s[24:25]
	s_nop 0
	v_addc_co_u32_e64 v61, s[12:13], 0, v61, s[12:13]
	v_subrev_u32_e32 v200, s18, v1
	v_bfe_u32 v202, v200, 12, 1
	v_lshlrev_b32_e32 v202, 21, v202
	v_bfe_u32 v201, v200, 4, 8
	v_lshl_add_u32 v202, v201, 11, v202
	v_and_b32_e32 v201, 15, v200
	v_lshl_add_u32 v202, v201, 6, v202
	v_and_b32_e32 v208, 63, v0
	v_lshrrev_b32_e32 v209, 5, v208
	v_lshl_add_u32 v202, v209, 19, v202
	v_bfe_u32 v209, v208, 4, 1
	v_lshl_add_u32 v202, v209, 10, v202
	v_and_b32_e32 v209, 15, v208
	v_lshl_add_u32 v202, v209, 2, v202
	v_add_u32_e32 v202, 0x13100000, v202
	v_mov_b32_e32 v203, 0
	v_add_u32_e32 v206, 0x100000, v202
	v_mov_b32_e32 v207, 0
	v_lshl_add_u64 v[204:205], v[202:203], 0, s[70:71]
	v_lshl_add_u64 v[206:207], v[206:207], 0, s[70:71]
	global_store_dword v[204:205], v63, off
	v_mul_f32_e32 v63, 0x45800000, v62
	v_cndmask_b32_e32 v62, v62, v63, vcc
	v_pk_mul_f32 v[62:63], v[62:63], v[68:69] op_sel_hi:[0,1]
	v_pk_mul_f32 v[62:63], v[6:7], v[62:63]
	v_cmp_lt_i32_e32 vcc, s74, v1
	v_cvt_pk_bf16_f32 v62, v62, v63
	s_or_b64 s[30:31], vcc, s[30:31]
	global_store_dword v[206:207], v62, off
	s_andn2_b64 exec, exec, s[30:31]
	s_cbranch_execz .LBB0_203

.LBB0_203:
	s_or_b64 exec, exec, s[16:17]
	s_load_dword s6, s[0:1], 0xd8
	v_and_b32_e32 v1, 63, v0
	v_lshlrev_b32_e32 v2, 1, v1
	v_lshlrev_b32_e32 v3, 6, v1
	v_readfirstlane_b32 s7, v130
	s_lshl_b32 s8, s2, 3
	s_nop 0
	s_add_u32 s8, s8, s7
	s_waitcnt lgkmcnt(0)
	s_lshl_b32 s6, s6, 3
	s_cmp_lt_u32 s8, 0x400
	s_cbranch_scc0 .Lvb_done
.Lvb_loop:
	s_lshr_b32 s9, s8, 9
	s_bfe_u32 s10, s8, 0x70002
	s_and_b32 s11, s8, 3
	s_lshl_b32 s12, s9, 7
	s_add_u32 s12, s12, s10
	s_mul_i32 s12, s12, 0x50000
	s_lshl_b32 s13, s11, 7
	s_add_u32 s12, s12, s13
	s_add_u32 s12, s12, 0x2600
	s_add_u32 s16, s70, s12
	s_addc_u32 s17, s71, 0
	s_add_u32 s16, s16, 0x7900000
	s_addc_u32 s17, s17, 0
	global_load_ushort v10, v2, s[16:17]
	s_add_u32 s16, s16, 0x2800
	s_addc_u32 s17, s17, 0
	global_load_ushort v11, v2, s[16:17]
	s_add_u32 s16, s16, 0x2800
	s_addc_u32 s17, s17, 0
	global_load_ushort v12, v2, s[16:17]
	s_add_u32 s16, s16, 0x2800
	s_addc_u32 s17, s17, 0
	global_load_ushort v13, v2, s[16:17]
	s_add_u32 s16, s16, 0x2800
	s_addc_u32 s17, s17, 0
	global_load_ushort v14, v2, s[16:17]
	s_add_u32 s16, s16, 0x2800
	s_addc_u32 s17, s17, 0
	global_load_ushort v15, v2, s[16:17]
	s_add_u32 s16, s16, 0x2800
	s_addc_u32 s17, s17, 0
	global_load_ushort v16, v2, s[16:17]
	s_add_u32 s16, s16, 0x2800
	s_addc_u32 s17, s17, 0
	global_load_ushort v17, v2, s[16:17]
	s_add_u32 s16, s16, 0x2800
	s_addc_u32 s17, s17, 0
	global_load_ushort v18, v2, s[16:17]
	s_add_u32 s16, s16, 0x2800
	s_addc_u32 s17, s17, 0
	global_load_ushort v19, v2, s[16:17]
	s_add_u32 s16, s16, 0x2800
	s_addc_u32 s17, s17, 0
	global_load_ushort v20, v2, s[16:17]
	s_add_u32 s16, s16, 0x2800
	s_addc_u32 s17, s17, 0
	global_load_ushort v21, v2, s[16:17]
	s_add_u32 s16, s16, 0x2800
	s_addc_u32 s17, s17, 0
	global_load_ushort v22, v2, s[16:17]
	s_add_u32 s16, s16, 0x2800
	s_addc_u32 s17, s17, 0
	global_load_ushort v23, v2, s[16:17]
	s_add_u32 s16, s16, 0x2800
	s_addc_u32 s17, s17, 0
	global_load_ushort v24, v2, s[16:17]
	s_add_u32 s16, s16, 0x2800
	s_addc_u32 s17, s17, 0
	global_load_ushort v25, v2, s[16:17]
	s_add_u32 s16, s16, 0x2800
	s_addc_u32 s17, s17, 0
	global_load_ushort v26, v2, s[16:17]
	s_add_u32 s16, s16, 0x2800
	s_addc_u32 s17, s17, 0
	global_load_ushort v27, v2, s[16:17]
	s_add_u32 s16, s16, 0x2800
	s_addc_u32 s17, s17, 0
	global_load_ushort v28, v2, s[16:17]
	s_add_u32 s16, s16, 0x2800
	s_addc_u32 s17, s17, 0
	global_load_ushort v29, v2, s[16:17]
	s_add_u32 s16, s16, 0x2800
	s_addc_u32 s17, s17, 0
	global_load_ushort v30, v2, s[16:17]
	s_add_u32 s16, s16, 0x2800
	s_addc_u32 s17, s17, 0
	global_load_ushort v31, v2, s[16:17]
	s_add_u32 s16, s16, 0x2800
	s_addc_u32 s17, s17, 0
	global_load_ushort v32, v2, s[16:17]
	s_add_u32 s16, s16, 0x2800
	s_addc_u32 s17, s17, 0
	global_load_ushort v33, v2, s[16:17]
	s_add_u32 s16, s16, 0x2800
	s_addc_u32 s17, s17, 0
	global_load_ushort v34, v2, s[16:17]
	s_add_u32 s16, s16, 0x2800
	s_addc_u32 s17, s17, 0
	global_load_ushort v35, v2, s[16:17]
	s_add_u32 s16, s16, 0x2800
	s_addc_u32 s17, s17, 0
	global_load_ushort v36, v2, s[16:17]
	s_add_u32 s16, s16, 0x2800
	s_addc_u32 s17, s17, 0
	global_load_ushort v37, v2, s[16:17]
	s_add_u32 s16, s16, 0x2800
	s_addc_u32 s17, s17, 0
	global_load_ushort v38, v2, s[16:17]
	s_add_u32 s16, s16, 0x2800
	s_addc_u32 s17, s17, 0
	global_load_ushort v39, v2, s[16:17]
	s_add_u32 s16, s16, 0x2800
	s_addc_u32 s17, s17, 0
	global_load_ushort v40, v2, s[16:17]
	s_add_u32 s16, s16, 0x2800
	s_addc_u32 s17, s17, 0
	global_load_ushort v41, v2, s[16:17]
	s_lshl_b32 s12, s9, 2
	s_add_u32 s12, s12, s11
	s_lshl_b32 s12, s12, 7
	s_add_u32 s12, s12, s10
	s_lshl_b32 s12, s12, 12
	s_add_u32 s18, s70, s12
	s_addc_u32 s19, s71, 0
	s_add_u32 s18, s18, 0x13500000
	s_addc_u32 s19, s19, 0
	s_waitcnt vmcnt(0)
	v_lshl_or_b32 v50, v11, 16, v10
	v_lshl_or_b32 v51, v13, 16, v12
	v_lshl_or_b32 v52, v27, 16, v26
	v_lshl_or_b32 v53, v29, 16, v28
	v_lshl_or_b32 v54, v15, 16, v14
	v_lshl_or_b32 v55, v17, 16, v16
	v_lshl_or_b32 v56, v31, 16, v30
	v_lshl_or_b32 v57, v33, 16, v32
	v_lshl_or_b32 v58, v19, 16, v18
	v_lshl_or_b32 v59, v21, 16, v20
	v_lshl_or_b32 v60, v35, 16, v34
	v_lshl_or_b32 v61, v37, 16, v36
	v_lshl_or_b32 v62, v23, 16, v22
	v_lshl_or_b32 v63, v25, 16, v24
	v_lshl_or_b32 v64, v39, 16, v38
	v_lshl_or_b32 v65, v41, 16, v40
	global_store_dwordx4 v3, v[50:53], s[18:19]
	global_store_dwordx4 v3, v[54:57], s[18:19] offset:16
	global_store_dwordx4 v3, v[58:61], s[18:19] offset:32
	global_store_dwordx4 v3, v[62:65], s[18:19] offset:48
	s_add_u32 s8, s8, s6
	s_cmp_lt_u32 s8, 0x400
	s_cbranch_scc1 .Lvb_loop

.LBB0_380:
	s_cmp_lt_i32 s34, 6
	s_cselect_b64 s[8:9], -1, 0
	v_writelane_b32 v255, s8, 2
	s_and_b64 s[6:7], s[8:9], s[6:7]
	s_andn2_b64 vcc, exec, s[6:7]
	v_writelane_b32 v255, s9, 3
	s_cbranch_vccnz .LBB0_571
	s_cmp_gt_i32 s2, 31
	s_cbranch_scc0 .LBB0_403
	v_and_b32_e32 v1, 63, v0
	v_and_b32_e32 v14, 15, v1
	v_lshrrev_b32_e32 v5, 4, v1
	v_xor_b32_e32 v11, 16, v1
	v_lshlrev_b32_e32 v11, 2, v11
	v_xor_b32_e32 v12, 32, v1
	v_lshlrev_b32_e32 v12, 2, v12
	v_lshlrev_b32_e32 v13, 11, v14
	v_lshl_add_u32 v13, v5, 4, v13
	v_lshlrev_b32_e32 v15, 4, v5
	v_lshlrev_b32_e32 v6, 2, v5
	v_sub_u32_e32 v7, v14, v6
	v_add_u32_e32 v7, 0x90, v7
	v_cvt_f32_i32_e32 v16, v7
	v_lshlrev_b32_e32 v17, 13, v5
	v_lshl_add_u32 v17, v14, 1, v17
	v_add_u32_e32 v18, 0x1000, v17
	v_lshlrev_b32_e32 v19, 6, v14
	v_lshl_add_u32 v19, v5, 4, v19
	v_mov_b32_e32 v20, v6
	v_mov_b32_e32 v133, 0xf149f2ca
	v_add_u32_e32 v7, 0, v6
	v_cmp_lt_u32_e64 s[74:75], v14, v7
	v_cmp_ge_u32_e64 s[82:83], v14, v7
	v_add_u32_e32 v7, 1, v6
	v_cmp_lt_u32_e64 s[76:77], v14, v7
	v_cmp_ge_u32_e64 s[84:85], v14, v7
	v_add_u32_e32 v7, 2, v6
	v_cmp_lt_u32_e64 s[78:79], v14, v7
	v_cmp_ge_u32_e64 s[86:87], v14, v7
	v_add_u32_e32 v7, 3, v6
	v_cmp_lt_u32_e64 s[80:81], v14, v7
	v_cmp_ge_u32_e64 s[88:89], v14, v7
	s_load_dword s6, s[0:1], 0xd8
	v_readfirstlane_b32 s7, v130
	s_sub_u32 s3, s2, 32
	s_lshl_b32 s3, s3, 3
	s_nop 0
	s_add_u32 s3, s3, s7
	s_waitcnt lgkmcnt(0)
	s_sub_u32 s6, s6, 32
	s_lshl_b32 s6, s6, 3
.Lat_loop:
	s_and_b32 s27, s3, 15
	s_bfe_u32 s28, s3, 0x80004
	s_lshr_b32 s29, s3, 12
	s_lshr_b32 s30, s27, 2
	s_lshl_b32 s31, s28, 4
	s_lshl_b32 s93, s27, 2
	s_load_dword s26, s[44:45], s93
	s_lshl_b32 s90, s29, 12
	s_add_u32 s90, s90, s31
	s_lshl_b32 s91, s90, 11
	s_lshl_b32 s92, s27, 7
	s_add_u32 s91, s91, s92
	s_add_u32 s8, s68, s91
	s_addc_u32 s9, s69, 0
	s_add_u32 s8, s8, 0x3000000
	s_addc_u32 s9, s9, 0
	s_add_u32 s20, s70, s91
	s_addc_u32 s21, s71, 0
	s_add_u32 s20, s20, 0x13900000
	s_addc_u32 s21, s21, 0
	s_lshl_b32 s94, s29, 2
	s_add_u32 s94, s94, s30
	s_lshl_b32 s94, s94, 19
	s_add_u32 s10, s70, s94
	s_addc_u32 s11, s71, 0
	s_add_u32 s10, s10, 0x13100000
	s_addc_u32 s11, s11, 0
	s_lshl_b32 s94, s29, 2
	s_add_u32 s94, s94, s30
	s_lshl_b32 s94, s94, 19
	s_add_u32 s12, s70, s94
	s_addc_u32 s13, s71, 0
	s_add_u32 s12, s12, 0x13500000
	s_addc_u32 s13, s13, 0
	s_add_i32 s22, s31, 0xffffff70
	s_sub_i32 s23, 9, s28
	s_max_i32 s23, s23, 0
	s_add_u32 s24, s27, 1
	v_cvt_f32_u32_e32 v21, s24
	v_mul_f32_e32 v21, -0.5, v21
	v_exp_f32_e32 v132, v21
	global_load_dwordx4 v[30:33], v13, s[8:9]
	global_load_dwordx4 v[34:37], v13, s[8:9] offset:64
	s_add_i32 s15, s28, -9
	s_max_i32 s15, s15, 0
	s_lshl_b32 s15, s15, 11
	s_add_u32 s16, s10, s15
	s_addc_u32 s17, s11, 0
	global_load_dwordx4 v[40:43], v19, s[16:17]
	global_load_dwordx4 v[44:47], v19, s[16:17] offset:1024
	s_add_i32 s15, s28, -8
	s_max_i32 s15, s15, 0
	s_lshl_b32 s15, s15, 11
	s_add_u32 s16, s10, s15
	s_addc_u32 s17, s11, 0
	global_load_dwordx4 v[48:51], v19, s[16:17]
	global_load_dwordx4 v[52:55], v19, s[16:17] offset:1024
	s_add_i32 s15, s28, -7
	s_max_i32 s15, s15, 0
	s_lshl_b32 s15, s15, 11
	s_add_u32 s16, s10, s15
	s_addc_u32 s17, s11, 0
	global_load_dwordx4 v[56:59], v19, s[16:17]
	global_load_dwordx4 v[60:63], v19, s[16:17] offset:1024
	s_add_i32 s15, s28, -6
	s_max_i32 s15, s15, 0
	s_lshl_b32 s15, s15, 11
	s_add_u32 s16, s10, s15
	s_addc_u32 s17, s11, 0
	global_load_dwordx4 v[64:67], v19, s[16:17]
	global_load_dwordx4 v[68:71], v19, s[16:17] offset:1024
	s_add_i32 s15, s28, -5
	s_max_i32 s15, s15, 0
	s_lshl_b32 s15, s15, 11
	s_add_u32 s16, s10, s15
	s_addc_u32 s17, s11, 0
	global_load_dwordx4 v[72:75], v19, s[16:17]
	global_load_dwordx4 v[76:79], v19, s[16:17] offset:1024
	s_add_i32 s15, s28, -4
	s_max_i32 s15, s15, 0
	s_lshl_b32 s15, s15, 11
	s_add_u32 s16, s10, s15
	s_addc_u32 s17, s11, 0
	global_load_dwordx4 v[80:83], v19, s[16:17]
	global_load_dwordx4 v[84:87], v19, s[16:17] offset:1024
	s_add_i32 s15, s28, -3
	s_max_i32 s15, s15, 0
	s_lshl_b32 s15, s15, 11
	s_add_u32 s16, s10, s15
	s_addc_u32 s17, s11, 0
	global_load_dwordx4 v[88:91], v19, s[16:17]
	global_load_dwordx4 v[92:95], v19, s[16:17] offset:1024
	s_add_i32 s15, s28, -2
	s_max_i32 s15, s15, 0
	s_lshl_b32 s15, s15, 11
	s_add_u32 s16, s10, s15
	s_addc_u32 s17, s11, 0
	global_load_dwordx4 v[96:99], v19, s[16:17]
	global_load_dwordx4 v[100:103], v19, s[16:17] offset:1024
	s_add_i32 s15, s28, -1
	s_max_i32 s15, s15, 0
	s_lshl_b32 s15, s15, 11
	s_add_u32 s16, s10, s15
	s_addc_u32 s17, s11, 0
	global_load_dwordx4 v[104:107], v19, s[16:17]
	global_load_dwordx4 v[108:111], v19, s[16:17] offset:1024
	s_add_i32 s15, s28, 0
	s_max_i32 s15, s15, 0
	s_lshl_b32 s15, s15, 11
	s_add_u32 s16, s10, s15
	s_addc_u32 s17, s11, 0
	global_load_dwordx4 v[112:115], v19, s[16:17]
	global_load_dwordx4 v[116:119], v19, s[16:17] offset:1024
	s_add_i32 s14, s28, -8
	s_ashr_i32 s14, s14, 1
	s_add_i32 s15, s14, 0
	s_max_i32 s15, s15, 0
	s_min_i32 s15, s15, 0x7f
	s_lshl_b32 s15, s15, 12
	s_add_u32 s16, s12, s15
	s_addc_u32 s17, s13, 0
	global_load_dwordx4 v[160:163], v19, s[16:17]
	global_load_dwordx4 v[164:167], v19, s[16:17] offset:1024
	global_load_dwordx4 v[168:171], v19, s[16:17] offset:2048
	global_load_dwordx4 v[172:175], v19, s[16:17] offset:3072
	s_add_i32 s15, s14, 1
	s_max_i32 s15, s15, 0
	s_min_i32 s15, s15, 0x7f
	s_lshl_b32 s15, s15, 12
	s_add_u32 s16, s12, s15
	s_addc_u32 s17, s13, 0
	global_load_dwordx4 v[176:179], v19, s[16:17]
	global_load_dwordx4 v[180:183], v19, s[16:17] offset:1024
	global_load_dwordx4 v[184:187], v19, s[16:17] offset:2048
	global_load_dwordx4 v[188:191], v19, s[16:17] offset:3072
	s_add_i32 s15, s14, 2
	s_max_i32 s15, s15, 0
	s_min_i32 s15, s15, 0x7f
	s_lshl_b32 s15, s15, 12
	s_add_u32 s16, s12, s15
	s_addc_u32 s17, s13, 0
	global_load_dwordx4 v[192:195], v19, s[16:17]
	global_load_dwordx4 v[196:199], v19, s[16:17] offset:1024
	global_load_dwordx4 v[200:203], v19, s[16:17] offset:2048
	global_load_dwordx4 v[204:207], v19, s[16:17] offset:3072
	s_add_i32 s15, s14, 3
	s_max_i32 s15, s15, 0
	s_min_i32 s15, s15, 0x7f
	s_lshl_b32 s15, s15, 12
	s_add_u32 s16, s12, s15
	s_addc_u32 s17, s13, 0
	global_load_dwordx4 v[208:211], v19, s[16:17]
	global_load_dwordx4 v[212:215], v19, s[16:17] offset:1024
	global_load_dwordx4 v[216:219], v19, s[16:17] offset:2048
	global_load_dwordx4 v[220:223], v19, s[16:17] offset:3072
	s_add_i32 s15, s14, 4
	s_max_i32 s15, s15, 0
	s_min_i32 s15, s15, 0x7f
	s_lshl_b32 s15, s15, 12
	s_add_u32 s16, s12, s15
	s_addc_u32 s17, s13, 0
	global_load_dwordx4 v[224:227], v19, s[16:17]
	global_load_dwordx4 v[228:231], v19, s[16:17] offset:1024
	global_load_dwordx4 v[232:235], v19, s[16:17] offset:2048
	global_load_dwordx4 v[236:239], v19, s[16:17] offset:3072
	v_sub_f32_e32 v132, 0, v132
	s_waitcnt lgkmcnt(0)
	v_mov_b32_e32 v128, s26
	s_waitcnt vmcnt(38)
	v_mfma_f32_16x16x32_bf16 v[40:43], v[40:43], v[30:33], 0
	v_mfma_f32_16x16x32_bf16 v[40:43], v[44:47], v[34:37], v[40:43]
	s_waitcnt vmcnt(36)
	v_mfma_f32_16x16x32_bf16 v[48:51], v[48:51], v[30:33], 0
	v_mfma_f32_16x16x32_bf16 v[48:51], v[52:55], v[34:37], v[48:51]
	s_waitcnt vmcnt(34)
	v_mfma_f32_16x16x32_bf16 v[56:59], v[56:59], v[30:33], 0
	v_mfma_f32_16x16x32_bf16 v[56:59], v[60:63], v[34:37], v[56:59]
	s_waitcnt vmcnt(32)
	v_mfma_f32_16x16x32_bf16 v[64:67], v[64:67], v[30:33], 0
	v_mfma_f32_16x16x32_bf16 v[64:67], v[68:71], v[34:37], v[64:67]
	s_waitcnt vmcnt(30)
	v_mfma_f32_16x16x32_bf16 v[72:75], v[72:75], v[30:33], 0
	v_mfma_f32_16x16x32_bf16 v[72:75], v[76:79], v[34:37], v[72:75]
	s_waitcnt vmcnt(28)
	v_mfma_f32_16x16x32_bf16 v[80:83], v[80:83], v[30:33], 0
	v_mfma_f32_16x16x32_bf16 v[80:83], v[84:87], v[34:37], v[80:83]
	s_waitcnt vmcnt(26)
	v_mfma_f32_16x16x32_bf16 v[88:91], v[88:91], v[30:33], 0
	v_mfma_f32_16x16x32_bf16 v[88:91], v[92:95], v[34:37], v[88:91]
	s_waitcnt vmcnt(24)
	v_mfma_f32_16x16x32_bf16 v[96:99], v[96:99], v[30:33], 0
	v_mfma_f32_16x16x32_bf16 v[96:99], v[100:103], v[34:37], v[96:99]
	s_waitcnt vmcnt(22)
	v_mfma_f32_16x16x32_bf16 v[104:107], v[104:107], v[30:33], 0
	v_mfma_f32_16x16x32_bf16 v[104:107], v[108:111], v[34:37], v[104:107]
	s_waitcnt vmcnt(20)
	v_mfma_f32_16x16x32_bf16 v[112:115], v[112:115], v[30:33], 0
	v_mfma_f32_16x16x32_bf16 v[112:115], v[116:119], v[34:37], v[112:115]
	v_mov_b32_e32 v40, v133
	v_mov_b32_e32 v41, v133
	v_mov_b32_e32 v42, v133
	v_mov_b32_e32 v43, v133
	v_subrev_f32_e32 v21, 0x41800000, v16
	v_subrev_f32_e32 v22, 0x41880000, v16
	v_subrev_f32_e32 v23, 0x41900000, v16
	v_subrev_f32_e32 v24, 0x41980000, v16
	v_fma_f32 v48, v132, v21, v48
	v_fma_f32 v49, v132, v22, v49
	v_fma_f32 v50, v132, v23, v50
	v_fma_f32 v51, v132, v24, v51
	v_cndmask_b32_e64 v48, v133, v48, s[74:75]
	v_cndmask_b32_e64 v49, v133, v49, s[76:77]
	v_cndmask_b32_e64 v50, v133, v50, s[78:79]
	v_cndmask_b32_e64 v51, v133, v51, s[80:81]
	s_cmp_lt_u32 s23, 2
	s_cbranch_scc1 .Lat_ok_1
	v_mov_b32_e32 v48, v133
	v_mov_b32_e32 v49, v133
	v_mov_b32_e32 v50, v133
	v_mov_b32_e32 v51, v133

.Lat_ok_8:
	v_max3_f32 v128, v128, v104, v105
	v_max3_f32 v128, v128, v106, v107
	v_subrev_f32_e32 v21, 0x43100000, v16
	v_subrev_f32_e32 v22, 0x43110000, v16
	v_subrev_f32_e32 v23, 0x43120000, v16
	v_subrev_f32_e32 v24, 0x43130000, v16
	v_fma_f32 v112, v132, v21, v112
	v_fma_f32 v113, v132, v22, v113
	v_fma_f32 v114, v132, v23, v114
	v_fma_f32 v115, v132, v24, v115
	v_cndmask_b32_e64 v112, v133, v112, s[82:83]
	v_cndmask_b32_e64 v113, v133, v113, s[84:85]
	v_cndmask_b32_e64 v114, v133, v114, s[86:87]
	v_cndmask_b32_e64 v115, v133, v115, s[88:89]
	v_max3_f32 v128, v128, v112, v113
	v_max3_f32 v128, v128, v114, v115
	v_max_f32_e32 v128, v128, v128
	ds_bpermute_b32 v21, v11, v128
	s_waitcnt lgkmcnt(0)
	v_max_f32_e32 v21, v21, v21
	v_max_f32_e32 v128, v128, v21
	ds_bpermute_b32 v21, v12, v128
	s_waitcnt lgkmcnt(0)
	v_max_f32_e32 v21, v21, v21
	v_max_f32_e32 v128, v128, v21
	v_mov_b32_e32 v129, 0
	v_sub_f32_e32 v40, v40, v128
	v_sub_f32_e32 v41, v41, v128
	v_sub_f32_e32 v42, v42, v128
	v_sub_f32_e32 v43, v43, v128
	v_sub_f32_e32 v48, v48, v128
	v_sub_f32_e32 v49, v49, v128
	v_sub_f32_e32 v50, v50, v128
	v_sub_f32_e32 v51, v51, v128
	v_sub_f32_e32 v56, v56, v128
	v_sub_f32_e32 v57, v57, v128
	v_sub_f32_e32 v58, v58, v128
	v_sub_f32_e32 v59, v59, v128
	v_sub_f32_e32 v64, v64, v128
	v_sub_f32_e32 v65, v65, v128
	v_sub_f32_e32 v66, v66, v128
	v_sub_f32_e32 v67, v67, v128
	v_sub_f32_e32 v72, v72, v128
	v_sub_f32_e32 v73, v73, v128
	v_sub_f32_e32 v74, v74, v128
	v_sub_f32_e32 v75, v75, v128
	v_sub_f32_e32 v80, v80, v128
	v_sub_f32_e32 v81, v81, v128
	v_sub_f32_e32 v82, v82, v128
	v_sub_f32_e32 v83, v83, v128
	v_sub_f32_e32 v88, v88, v128
	v_sub_f32_e32 v89, v89, v128
	v_sub_f32_e32 v90, v90, v128
	v_sub_f32_e32 v91, v91, v128
	v_sub_f32_e32 v96, v96, v128
	v_sub_f32_e32 v97, v97, v128
	v_sub_f32_e32 v98, v98, v128
	v_sub_f32_e32 v99, v99, v128
	v_sub_f32_e32 v104, v104, v128
	v_sub_f32_e32 v105, v105, v128
	v_sub_f32_e32 v106, v106, v128
	v_sub_f32_e32 v107, v107, v128
	v_sub_f32_e32 v112, v112, v128
	v_sub_f32_e32 v113, v113, v128
	v_sub_f32_e32 v114, v114, v128
	v_sub_f32_e32 v115, v115, v128
	v_mul_f32_e32 v40, 0x3fb8aa3b, v40
	v_mul_f32_e32 v41, 0x3fb8aa3b, v41
	v_mul_f32_e32 v42, 0x3fb8aa3b, v42
	v_mul_f32_e32 v43, 0x3fb8aa3b, v43
	v_mul_f32_e32 v48, 0x3fb8aa3b, v48
	v_mul_f32_e32 v49, 0x3fb8aa3b, v49
	v_mul_f32_e32 v50, 0x3fb8aa3b, v50
	v_mul_f32_e32 v51, 0x3fb8aa3b, v51
	v_mul_f32_e32 v56, 0x3fb8aa3b, v56
	v_mul_f32_e32 v57, 0x3fb8aa3b, v57
	v_mul_f32_e32 v58, 0x3fb8aa3b, v58
	v_mul_f32_e32 v59, 0x3fb8aa3b, v59
	v_mul_f32_e32 v64, 0x3fb8aa3b, v64
	v_mul_f32_e32 v65, 0x3fb8aa3b, v65
	v_mul_f32_e32 v66, 0x3fb8aa3b, v66
	v_mul_f32_e32 v67, 0x3fb8aa3b, v67
	v_mul_f32_e32 v72, 0x3fb8aa3b, v72
	v_mul_f32_e32 v73, 0x3fb8aa3b, v73
	v_mul_f32_e32 v74, 0x3fb8aa3b, v74
	v_mul_f32_e32 v75, 0x3fb8aa3b, v75
	v_mul_f32_e32 v80, 0x3fb8aa3b, v80
	v_mul_f32_e32 v81, 0x3fb8aa3b, v81
	v_mul_f32_e32 v82, 0x3fb8aa3b, v82
	v_mul_f32_e32 v83, 0x3fb8aa3b, v83
	v_mul_f32_e32 v88, 0x3fb8aa3b, v88
	v_mul_f32_e32 v89, 0x3fb8aa3b, v89
	v_mul_f32_e32 v90, 0x3fb8aa3b, v90
	v_mul_f32_e32 v91, 0x3fb8aa3b, v91
	v_mul_f32_e32 v96, 0x3fb8aa3b, v96
	v_mul_f32_e32 v97, 0x3fb8aa3b, v97
	v_mul_f32_e32 v98, 0x3fb8aa3b, v98
	v_mul_f32_e32 v99, 0x3fb8aa3b, v99
	v_mul_f32_e32 v104, 0x3fb8aa3b, v104
	v_mul_f32_e32 v105, 0x3fb8aa3b, v105
	v_mul_f32_e32 v106, 0x3fb8aa3b, v106
	v_mul_f32_e32 v107, 0x3fb8aa3b, v107
	v_mul_f32_e32 v112, 0x3fb8aa3b, v112
	v_mul_f32_e32 v113, 0x3fb8aa3b, v113
	v_mul_f32_e32 v114, 0x3fb8aa3b, v114
	v_mul_f32_e32 v115, 0x3fb8aa3b, v115
	v_exp_f32_e32 v40, v40
	v_exp_f32_e32 v41, v41
	v_exp_f32_e32 v42, v42
	v_exp_f32_e32 v43, v43
	v_exp_f32_e32 v48, v48
	v_exp_f32_e32 v49, v49
	v_exp_f32_e32 v50, v50
	v_exp_f32_e32 v51, v51
	v_exp_f32_e32 v56, v56
	v_exp_f32_e32 v57, v57
	v_exp_f32_e32 v58, v58
	v_exp_f32_e32 v59, v59
	v_exp_f32_e32 v64, v64
	v_exp_f32_e32 v65, v65
	v_exp_f32_e32 v66, v66
	v_exp_f32_e32 v67, v67
	v_exp_f32_e32 v72, v72
	v_exp_f32_e32 v73, v73
	v_exp_f32_e32 v74, v74
	v_exp_f32_e32 v75, v75
	v_exp_f32_e32 v80, v80
	v_exp_f32_e32 v81, v81
	v_exp_f32_e32 v82, v82
	v_exp_f32_e32 v83, v83
	v_exp_f32_e32 v88, v88
	v_exp_f32_e32 v89, v89
	v_exp_f32_e32 v90, v90
	v_exp_f32_e32 v91, v91
	v_exp_f32_e32 v96, v96
	v_exp_f32_e32 v97, v97
	v_exp_f32_e32 v98, v98
	v_exp_f32_e32 v99, v99
	v_exp_f32_e32 v104, v104
	v_exp_f32_e32 v105, v105
	v_exp_f32_e32 v106, v106
	v_exp_f32_e32 v107, v107
	v_exp_f32_e32 v112, v112
	v_exp_f32_e32 v113, v113
	v_exp_f32_e32 v114, v114
	v_exp_f32_e32 v115, v115
	s_nop 0
	v_add_f32_e32 v129, v40, v129
	v_add_f32_e32 v129, v41, v129
	v_add_f32_e32 v129, v42, v129
	v_add_f32_e32 v129, v43, v129
	v_add_f32_e32 v129, v48, v129
	v_add_f32_e32 v129, v49, v129
	v_add_f32_e32 v129, v50, v129
	v_add_f32_e32 v129, v51, v129
	v_add_f32_e32 v129, v56, v129
	v_add_f32_e32 v129, v57, v129
	v_add_f32_e32 v129, v58, v129
	v_add_f32_e32 v129, v59, v129
	v_add_f32_e32 v129, v64, v129
	v_add_f32_e32 v129, v65, v129
	v_add_f32_e32 v129, v66, v129
	v_add_f32_e32 v129, v67, v129
	v_add_f32_e32 v129, v72, v129
	v_add_f32_e32 v129, v73, v129
	v_add_f32_e32 v129, v74, v129
	v_add_f32_e32 v129, v75, v129
	v_add_f32_e32 v129, v80, v129
	v_add_f32_e32 v129, v81, v129
	v_add_f32_e32 v129, v82, v129
	v_add_f32_e32 v129, v83, v129
	v_add_f32_e32 v129, v88, v129
	v_add_f32_e32 v129, v89, v129
	v_add_f32_e32 v129, v90, v129
	v_add_f32_e32 v129, v91, v129
	v_add_f32_e32 v129, v96, v129
	v_add_f32_e32 v129, v97, v129
	v_add_f32_e32 v129, v98, v129
	v_add_f32_e32 v129, v99, v129
	v_add_f32_e32 v129, v104, v129
	v_add_f32_e32 v129, v105, v129
	v_add_f32_e32 v129, v106, v129
	v_add_f32_e32 v129, v107, v129
	v_add_f32_e32 v129, v112, v129
	v_add_f32_e32 v129, v113, v129
	v_add_f32_e32 v129, v114, v129
	v_add_f32_e32 v129, v115, v129
	ds_bpermute_b32 v21, v11, v129
	s_waitcnt lgkmcnt(0)
	v_add_f32_e32 v129, v129, v21
	ds_bpermute_b32 v21, v12, v129
	s_waitcnt lgkmcnt(0)
	v_add_f32_e32 v129, v129, v21
	v_sub_f32_e32 v21, s26, v128
	v_mul_f32_e32 v21, 0x3fb8aa3b, v21
	v_exp_f32_e32 v21, v21
	s_nop 0
	v_add_f32_e32 v129, v21, v129
	v_div_scale_f32 v134, s[30:31], v129, v129, 1.0
	v_rcp_f32_e32 v135, v134
	s_nop 0
	v_fma_f32 v136, -v134, v135, 1.0
	v_fmac_f32_e32 v135, v136, v135
	v_div_scale_f32 v136, vcc, 1.0, v129, 1.0
	v_mul_f32_e32 v137, v136, v135
	v_fma_f32 v138, -v134, v137, v136
	v_fmac_f32_e32 v137, v138, v135
	v_fma_f32 v134, -v134, v137, v136
	v_div_fmas_f32 v134, v134, v135, v137
	v_div_fixup_f32 v131, v134, v129, 1.0
	v_mul_f32_e32 v40, v40, v131
	v_mul_f32_e32 v41, v41, v131
	v_mul_f32_e32 v42, v42, v131
	v_mul_f32_e32 v43, v43, v131
	v_mul_f32_e32 v48, v48, v131
	v_mul_f32_e32 v49, v49, v131
	v_mul_f32_e32 v50, v50, v131
	v_mul_f32_e32 v51, v51, v131
	v_mul_f32_e32 v56, v56, v131
	v_mul_f32_e32 v57, v57, v131
	v_mul_f32_e32 v58, v58, v131
	v_mul_f32_e32 v59, v59, v131
	v_mul_f32_e32 v64, v64, v131
	v_mul_f32_e32 v65, v65, v131
	v_mul_f32_e32 v66, v66, v131
	v_mul_f32_e32 v67, v67, v131
	v_mul_f32_e32 v72, v72, v131
	v_mul_f32_e32 v73, v73, v131
	v_mul_f32_e32 v74, v74, v131
	v_mul_f32_e32 v75, v75, v131
	v_mul_f32_e32 v80, v80, v131
	v_mul_f32_e32 v81, v81, v131
	v_mul_f32_e32 v82, v82, v131
	v_mul_f32_e32 v83, v83, v131
	v_mul_f32_e32 v88, v88, v131
	v_mul_f32_e32 v89, v89, v131
	v_mul_f32_e32 v90, v90, v131
	v_mul_f32_e32 v91, v91, v131
	v_mul_f32_e32 v96, v96, v131
	v_mul_f32_e32 v97, v97, v131
	v_mul_f32_e32 v98, v98, v131
	v_mul_f32_e32 v99, v99, v131
	v_mul_f32_e32 v104, v104, v131
	v_mul_f32_e32 v105, v105, v131
	v_mul_f32_e32 v106, v106, v131
	v_mul_f32_e32 v107, v107, v131
	v_mul_f32_e32 v112, v112, v131
	v_mul_f32_e32 v113, v113, v131
	v_mul_f32_e32 v114, v114, v131
	v_mul_f32_e32 v115, v115, v131
	s_bitcmp1_b32 s28, 0
	s_cbranch_scc0 .Lat_pv_odd
	v_cvt_pk_bf16_f32 v124, v40, v41
	v_cvt_pk_bf16_f32 v125, v42, v43
	v_cvt_pk_bf16_f32 v126, v48, v49
	v_cvt_pk_bf16_f32 v127, v50, v51
	s_waitcnt vmcnt(19)
	s_nop 0
	v_mfma_f32_16x16x32_bf16 v[240:243], v[124:127], v[160:163], 0
	s_waitcnt vmcnt(18)
	v_mfma_f32_16x16x32_bf16 v[244:247], v[124:127], v[164:167], 0
	s_waitcnt vmcnt(17)
	v_mfma_f32_16x16x32_bf16 v[248:251], v[124:127], v[168:171], 0
	s_waitcnt vmcnt(16)
	v_mfma_f32_16x16x32_bf16 v[120:123], v[124:127], v[172:175], 0
	v_cvt_pk_bf16_f32 v124, v56, v57
	v_cvt_pk_bf16_f32 v125, v58, v59
	v_cvt_pk_bf16_f32 v126, v64, v65
	v_cvt_pk_bf16_f32 v127, v66, v67
	s_waitcnt vmcnt(15)
	s_nop 0
	v_mfma_f32_16x16x32_bf16 v[240:243], v[124:127], v[176:179], v[240:243]
	s_waitcnt vmcnt(14)
	v_mfma_f32_16x16x32_bf16 v[244:247], v[124:127], v[180:183], v[244:247]
	s_waitcnt vmcnt(13)
	v_mfma_f32_16x16x32_bf16 v[248:251], v[124:127], v[184:187], v[248:251]
	s_waitcnt vmcnt(12)
	v_mfma_f32_16x16x32_bf16 v[120:123], v[124:127], v[188:191], v[120:123]
	v_cvt_pk_bf16_f32 v124, v72, v73
	v_cvt_pk_bf16_f32 v125, v74, v75
	v_cvt_pk_bf16_f32 v126, v80, v81
	v_cvt_pk_bf16_f32 v127, v82, v83
	s_waitcnt vmcnt(11)
	s_nop 0
	v_mfma_f32_16x16x32_bf16 v[240:243], v[124:127], v[192:195], v[240:243]
	s_waitcnt vmcnt(10)
	v_mfma_f32_16x16x32_bf16 v[244:247], v[124:127], v[196:199], v[244:247]
	s_waitcnt vmcnt(9)
	v_mfma_f32_16x16x32_bf16 v[248:251], v[124:127], v[200:203], v[248:251]
	s_waitcnt vmcnt(8)
	v_mfma_f32_16x16x32_bf16 v[120:123], v[124:127], v[204:207], v[120:123]
	v_cvt_pk_bf16_f32 v124, v88, v89
	v_cvt_pk_bf16_f32 v125, v90, v91
	v_cvt_pk_bf16_f32 v126, v96, v97
	v_cvt_pk_bf16_f32 v127, v98, v99
	s_waitcnt vmcnt(7)
	s_nop 0
	v_mfma_f32_16x16x32_bf16 v[240:243], v[124:127], v[208:211], v[240:243]
	s_waitcnt vmcnt(6)
	v_mfma_f32_16x16x32_bf16 v[244:247], v[124:127], v[212:215], v[244:247]
	s_waitcnt vmcnt(5)
	v_mfma_f32_16x16x32_bf16 v[248:251], v[124:127], v[216:219], v[248:251]
	s_waitcnt vmcnt(4)
	v_mfma_f32_16x16x32_bf16 v[120:123], v[124:127], v[220:223], v[120:123]
	v_cvt_pk_bf16_f32 v124, v104, v105
	v_cvt_pk_bf16_f32 v125, v106, v107
	v_cvt_pk_bf16_f32 v126, v112, v113
	v_cvt_pk_bf16_f32 v127, v114, v115
	s_waitcnt vmcnt(3)
	s_nop 0
	v_mfma_f32_16x16x32_bf16 v[240:243], v[124:127], v[224:227], v[240:243]
	s_waitcnt vmcnt(2)
	v_mfma_f32_16x16x32_bf16 v[244:247], v[124:127], v[228:231], v[244:247]
	s_waitcnt vmcnt(1)
	v_mfma_f32_16x16x32_bf16 v[248:251], v[124:127], v[232:235], v[248:251]
	s_waitcnt vmcnt(0)
	v_mfma_f32_16x16x32_bf16 v[120:123], v[124:127], v[236:239], v[120:123]
	s_branch .Lat_pv_done
.Lat_pv_odd:
	v_cvt_pk_bf16_f32 v124, v48, v49
	v_cvt_pk_bf16_f32 v125, v50, v51
	v_cvt_pk_bf16_f32 v126, v56, v57
	v_cvt_pk_bf16_f32 v127, v58, v59
	s_waitcnt vmcnt(19)
	s_nop 0
	v_mfma_f32_16x16x32_bf16 v[240:243], v[124:127], v[160:163], 0
	s_waitcnt vmcnt(18)
	v_mfma_f32_16x16x32_bf16 v[244:247], v[124:127], v[164:167], 0
	s_waitcnt vmcnt(17)
	v_mfma_f32_16x16x32_bf16 v[248:251], v[124:127], v[168:171], 0
	s_waitcnt vmcnt(16)
	v_mfma_f32_16x16x32_bf16 v[120:123], v[124:127], v[172:175], 0
	v_cvt_pk_bf16_f32 v124, v64, v65
	v_cvt_pk_bf16_f32 v125, v66, v67
	v_cvt_pk_bf16_f32 v126, v72, v73
	v_cvt_pk_bf16_f32 v127, v74, v75
	s_waitcnt vmcnt(15)
	s_nop 0
	v_mfma_f32_16x16x32_bf16 v[240:243], v[124:127], v[176:179], v[240:243]
	s_waitcnt vmcnt(14)
	v_mfma_f32_16x16x32_bf16 v[244:247], v[124:127], v[180:183], v[244:247]
	s_waitcnt vmcnt(13)
	v_mfma_f32_16x16x32_bf16 v[248:251], v[124:127], v[184:187], v[248:251]
	s_waitcnt vmcnt(12)
	v_mfma_f32_16x16x32_bf16 v[120:123], v[124:127], v[188:191], v[120:123]
	v_cvt_pk_bf16_f32 v124, v80, v81
	v_cvt_pk_bf16_f32 v125, v82, v83
	v_cvt_pk_bf16_f32 v126, v88, v89
	v_cvt_pk_bf16_f32 v127, v90, v91
	s_waitcnt vmcnt(11)
	s_nop 0
	v_mfma_f32_16x16x32_bf16 v[240:243], v[124:127], v[192:195], v[240:243]
	s_waitcnt vmcnt(10)
	v_mfma_f32_16x16x32_bf16 v[244:247], v[124:127], v[196:199], v[244:247]
	s_waitcnt vmcnt(9)
	v_mfma_f32_16x16x32_bf16 v[248:251], v[124:127], v[200:203], v[248:251]
	s_waitcnt vmcnt(8)
	v_mfma_f32_16x16x32_bf16 v[120:123], v[124:127], v[204:207], v[120:123]
	v_cvt_pk_bf16_f32 v124, v96, v97
	v_cvt_pk_bf16_f32 v125, v98, v99
	v_cvt_pk_bf16_f32 v126, v104, v105
	v_cvt_pk_bf16_f32 v127, v106, v107
	s_waitcnt vmcnt(7)
	s_nop 0
	v_mfma_f32_16x16x32_bf16 v[240:243], v[124:127], v[208:211], v[240:243]
	s_waitcnt vmcnt(6)
	v_mfma_f32_16x16x32_bf16 v[244:247], v[124:127], v[212:215], v[244:247]
	s_waitcnt vmcnt(5)
	v_mfma_f32_16x16x32_bf16 v[248:251], v[124:127], v[216:219], v[248:251]
	s_waitcnt vmcnt(4)
	v_mfma_f32_16x16x32_bf16 v[120:123], v[124:127], v[220:223], v[120:123]
	v_cvt_pk_bf16_f32 v124, v112, v113
	v_cvt_pk_bf16_f32 v125, v114, v115
	v_mov_b32_e32 v126, 0
	v_mov_b32_e32 v127, 0
	s_waitcnt vmcnt(3)
	s_nop 0
	v_mfma_f32_16x16x32_bf16 v[240:243], v[124:127], v[224:227], v[240:243]
	s_waitcnt vmcnt(2)
	v_mfma_f32_16x16x32_bf16 v[244:247], v[124:127], v[228:231], v[244:247]
	s_waitcnt vmcnt(1)
	v_mfma_f32_16x16x32_bf16 v[248:251], v[124:127], v[232:235], v[248:251]
	s_waitcnt vmcnt(0)
	v_mfma_f32_16x16x32_bf16 v[120:123], v[124:127], v[236:239], v[120:123]
.Lat_pv_done:
	s_nop 7
	v_cvt_pk_bf16_f32 v22, v240, v240
	v_cvt_pk_bf16_f32 v23, v241, v241
	v_cvt_pk_bf16_f32 v24, v242, v242
	v_cvt_pk_bf16_f32 v25, v243, v243
	v_cvt_pk_bf16_f32 v26, v244, v244
	v_cvt_pk_bf16_f32 v27, v245, v245
	v_cvt_pk_bf16_f32 v28, v246, v246
	v_cvt_pk_bf16_f32 v29, v247, v247
	v_cvt_pk_bf16_f32 v134, v248, v248
	v_cvt_pk_bf16_f32 v135, v249, v249
	v_cvt_pk_bf16_f32 v136, v250, v250
	v_cvt_pk_bf16_f32 v137, v251, v251
	v_cvt_pk_bf16_f32 v138, v120, v120
	v_cvt_pk_bf16_f32 v139, v121, v121
	v_cvt_pk_bf16_f32 v150, v122, v122
	v_cvt_pk_bf16_f32 v151, v123, v123
	global_store_short v17, v22, s[20:21]
	global_store_short v17, v23, s[20:21] offset:2048
	global_store_short v18, v24, s[20:21]
	global_store_short v18, v25, s[20:21] offset:2048
	global_store_short v17, v26, s[20:21] offset:32
	global_store_short v17, v27, s[20:21] offset:2080
	global_store_short v18, v28, s[20:21] offset:32
	global_store_short v18, v29, s[20:21] offset:2080
	global_store_short v17, v134, s[20:21] offset:64
	global_store_short v17, v135, s[20:21] offset:2112
	global_store_short v18, v136, s[20:21] offset:64
	global_store_short v18, v137, s[20:21] offset:2112
	global_store_short v17, v138, s[20:21] offset:96
	global_store_short v17, v139, s[20:21] offset:2144
	global_store_short v18, v150, s[20:21] offset:96
	global_store_short v18, v151, s[20:21] offset:2144
	s_add_u32 s3, s3, s6
	s_cmp_lt_u32 s3, 0x2000
	s_cbranch_scc1 .Lat_loop
	v_and_b32_e32 v10, 15, v0
	s_add_u32 s74, s0, 0xd8
	s_addc_u32 s75, s1, 0
	v_mov_b64_e32 v[2:3], s[74:75]
	s_mov_b64 s[64:65], exec
